# speedup vs baseline: 1.0055x; 1.0055x over previous
; __device__ __forceinline__ f16v mfma16(h8 a, h8 b, f16v c) { return __builtin_amdgcn_mfma_f32_32x32x16_f16(a, b, c, 0, 0, 0); }
; template <int EQK, int EV, bool PF, class KP, class SC>
; __device__ __forceinline__ void flash_core(f16v (&o)[EV / 32], float& m_run, float& l_run, const h8 (&qf)[EQK / 16],
;                                            int kt0, int kt1, const KP& kp, const SC& sc, char* smem) {
;     ...
;       h8 pf[4];
; #pragma unroll
;       for (int i = 0; i < 8; ++i) { pf[0][i] = (h16)p0[i]; pf[1][i] = (h16)p0[8 + i]; pf[2][i] = (h16)p1[i]; pf[3][i] = (h16)p1[8 + i]; }
; #pragma unroll
;       for (int et = 0; et < EV / 32; ++et) {
;         const h16* vb = sV + (et * 32 + l31) * VLD + hi * 4;
; #pragma unroll
;         for (int ks = 0; ks < 4; ++ks) {
;           h4 lo = *(const h4*)(vb + ks * 16), hh = *(const h4*)(vb + ks * 16 + 8);
;           h8 vf = {lo[0], lo[1], lo[2], lo[3], hh[0], hh[1], hh[2], hh[3]};
;           o[et] = mfma16(vf, pf[ks], o[et]);
;         }
;       }
;     }
;     if (PF) {
;       if (more) lstore(cur ^ 1);
;       __syncthreads();
;       cur ^= 1;
;     } else if (more) {
;       __syncthreads();
;       gload(kt + 1); lstore(0);
;       __syncthreads();
;     }
.LBB0_1098:
	v_lshl_add_u32 v93, v147, 1, s41
	v_add_u32_e32 v93, v253, v93
	v_cvt_pk_f16_f32 v195, v194, v108
	v_cvt_pk_f16_f32 v194, v193, v102
	v_cvt_pk_f16_f32 v193, v192, v96
	v_cvt_pk_f16_f32 v192, v191, v0
	v_add_u32_e32 v254, v93, v139
	v_cvt_pk_f16_f32 v103, v103, v100
	v_cvt_pk_f16_f32 v100, v95, v14
	v_cvt_pk_f16_f32 v167, v111, v166
	v_cvt_pk_f16_f32 v166, v161, v164
	v_cvt_pk_f16_f32 v164, v101, v106
	v_cvt_pk_f16_f32 v106, v105, v110
	v_cvt_pk_f16_f32 v105, v99, v104
	v_cvt_pk_f16_f32 v104, v97, v98
	ds_read_b128 v[96:99], v254 offset:13824
	s_waitcnt lgkmcnt(0)
	v_mfma_f32_32x32x16_f16 v[48:63], v[96:99], v[192:195], v[48:63]
	ds_read_b128 v[96:99], v254 offset:13856
	v_cvt_pk_f16_f32 v165, v107, v160
	v_cvt_pk_f16_f32 v102, v89, v90
	v_cvt_pk_f16_f32 v101, v15, v88
	v_cvt_pk_f16_f32 v107, v109, v162
	s_waitcnt lgkmcnt(0)
	v_mfma_f32_32x32x16_f16 v[48:63], v[96:99], v[164:167], v[48:63]
	ds_read_b128 v[96:99], v254 offset:13888
	ds_read_b128 v[196:199], v254 offset:9216
	s_xor_b32 s33, s33, 1
	s_mul_i32 s41, s33, 0x6c00
	s_mov_b64 s[8:9], 0x80
	s_waitcnt lgkmcnt(1)
	v_mfma_f32_32x32x16_f16 v[48:63], v[96:99], v[100:103], v[48:63]
	ds_read_b128 v[96:99], v254 offset:13920
	v_add_f32_e32 v14, v92, v91
	v_fmac_f32_e32 v14, v190, v94
	ds_read_b128 v[88:91], v254 offset:18528
	s_sub_i32 s2, s2, 64
	v_add_u32_e32 v148, s8, v148
	v_add_u32_e32 v150, s8, v150
	s_waitcnt lgkmcnt(1)
	v_mfma_f32_32x32x16_f16 v[48:63], v[96:99], v[104:107], v[48:63]
	ds_read_b128 v[96:99], v254 offset:18432
	v_add_u32_e32 v152, s8, v152
	v_add_u32_e32 v154, s8, v154
	s_mov_b64 s[8:9], 0x40000
	v_add_u32_e32 v156, s8, v156
	v_add_u32_e32 v158, s8, v158
	s_cmpk_lg_i32 s2, 0xf040
	v_mfma_f32_32x32x16_f16 v[64:79], v[196:199], v[192:195], v[64:79]
	ds_read_b128 v[196:199], v254 offset:9248
	s_waitcnt lgkmcnt(1)
	v_mfma_f32_32x32x16_f16 v[32:47], v[96:99], v[192:195], v[32:47]
	ds_read_b128 v[96:99], v254 offset:18464
	s_waitcnt lgkmcnt(1)
	v_mfma_f32_32x32x16_f16 v[64:79], v[196:199], v[164:167], v[64:79]
	ds_read_b128 v[196:199], v254 offset:9280
	s_waitcnt lgkmcnt(1)
	v_mfma_f32_32x32x16_f16 v[32:47], v[96:99], v[164:167], v[32:47]
	ds_read_b128 v[96:99], v254 offset:18496
	s_waitcnt lgkmcnt(1)
	v_mfma_f32_32x32x16_f16 v[64:79], v[196:199], v[100:103], v[64:79]
	ds_read_b128 v[196:199], v254 offset:9312
	s_waitcnt lgkmcnt(1)
	v_mfma_f32_32x32x16_f16 v[32:47], v[96:99], v[100:103], v[32:47]
	ds_read_b128 v[92:95], v254 offset:23040
	ds_read_b128 v[96:99], v254 offset:23072
	ds_read_b128 v[108:111], v254 offset:23104
	ds_read_b128 v[160:163], v254 offset:23136
	v_lshlrev_b32_e32 v0, 1, v172
	v_add3_u32 v0, s41, v0, v173
	s_waitcnt vmcnt(5)
	ds_write_b128 v0, v[6:9]
	v_lshlrev_b32_e32 v0, 1, v174
	v_add3_u32 v0, s41, v0, v175
	s_waitcnt vmcnt(4)
	ds_write_b128 v0, v[2:5]
	s_waitcnt lgkmcnt(5)
	v_mfma_f32_32x32x16_f16 v[16:31], v[92:95], v[192:195], v[16:31]
	v_lshlrev_b32_e32 v0, 1, v182
	v_add3_u32 v0, s41, v0, v146
	s_waitcnt vmcnt(3)
	v_add_u32_e32 v254, v252, v0
	ds_write2_b64 v254, v[128:129], v[130:131] offset1:2
	v_lshlrev_b32_e32 v0, 1, v183
	v_add3_u32 v0, s41, v0, v146
	s_waitcnt vmcnt(2)
	v_add_u32_e32 v255, v252, v0
	ds_write2_b64 v255, v[10:11], v[12:13] offset1:2
	v_lshlrev_b32_e32 v0, 1, v184
	s_waitcnt lgkmcnt(6)
	v_mfma_f32_32x32x16_f16 v[16:31], v[96:99], v[164:167], v[16:31]
	v_add3_u32 v0, s41, v0, v146
	s_waitcnt vmcnt(1)
	v_add_u32_e32 v254, v252, v0
	ds_write2_b64 v254, v[84:85], v[86:87] offset1:2
	v_lshlrev_b32_e32 v0, 1, v185
	v_add3_u32 v0, s41, v0, v146
	s_waitcnt vmcnt(0)
	v_add_u32_e32 v255, v252, v0
	ds_write2_b64 v255, v[80:81], v[82:83] offset1:2
	s_waitcnt lgkmcnt(0)
	s_barrier
	v_mfma_f32_32x32x16_f16 v[16:31], v[108:111], v[100:103], v[16:31]
	v_mfma_f32_32x32x16_f16 v[64:79], v[196:199], v[104:107], v[64:79]
	v_mfma_f32_32x32x16_f16 v[32:47], v[88:91], v[104:107], v[32:47]
	v_mfma_f32_32x32x16_f16 v[16:31], v[160:163], v[104:107], v[16:31]
	v_mov_b32_e32 v190, v14
	s_cbranch_scc1 .LBB0_1096

; __device__ __forceinline__ f16v mfma16(h8 a, h8 b, f16v c) { return __builtin_amdgcn_mfma_f32_32x32x16_f16(a, b, c, 0, 0, 0); }
; template <int EQK, int EV, bool PF, class KP, class SC>
; __device__ __forceinline__ void flash_core(f16v (&o)[EV / 32], float& m_run, float& l_run, const h8 (&qf)[EQK / 16],
;                                            int kt0, int kt1, const KP& kp, const SC& sc, char* smem) {
;     ...
;       h8 pf[4];
; #pragma unroll
;       for (int i = 0; i < 8; ++i) { pf[0][i] = (h16)p0[i]; pf[1][i] = (h16)p0[8 + i]; pf[2][i] = (h16)p1[i]; pf[3][i] = (h16)p1[8 + i]; }
; #pragma unroll
;       for (int et = 0; et < EV / 32; ++et) {
;         const h16* vb = sV + (et * 32 + l31) * VLD + hi * 4;
; #pragma unroll
;         for (int ks = 0; ks < 4; ++ks) {
;           h4 lo = *(const h4*)(vb + ks * 16), hh = *(const h4*)(vb + ks * 16 + 8);
;           h8 vf = {lo[0], lo[1], lo[2], lo[3], hh[0], hh[1], hh[2], hh[3]};
;           o[et] = mfma16(vf, pf[ks], o[et]);
;         }
;       }
;     }
;     if (PF) {
;       if (more) lstore(cur ^ 1);
;       __syncthreads();
;       cur ^= 1;
;     } else if (more) {
;       __syncthreads();
;       gload(kt + 1); lstore(0);
;       __syncthreads();
;     }
.LBB0_1105:
	v_lshl_add_u32 v93, v166, 1, s15
	v_add_u32_e32 v93, v253, v93
	v_cvt_pk_f16_f32 v190, v190, v0
	v_add_u32_e32 v254, v93, v139
	v_cvt_pk_f16_f32 v103, v103, v100
	v_cvt_pk_f16_f32 v100, v95, v14
	v_cvt_pk_f16_f32 v191, v191, v96
	v_cvt_pk_f16_f32 v165, v111, v164
	v_cvt_pk_f16_f32 v164, v159, v162
	v_cvt_pk_f16_f32 v162, v101, v106
	v_cvt_pk_f16_f32 v106, v105, v110
	v_cvt_pk_f16_f32 v105, v99, v104
	v_cvt_pk_f16_f32 v104, v97, v98
	ds_read_b128 v[96:99], v254 offset:13824
	v_cvt_pk_f16_f32 v193, v193, v108
	v_cvt_pk_f16_f32 v192, v192, v102
	v_cvt_pk_f16_f32 v163, v107, v158
	v_cvt_pk_f16_f32 v102, v89, v90
	s_waitcnt lgkmcnt(0)
	v_mfma_f32_32x32x16_f16 v[48:63], v[96:99], v[190:193], v[48:63]
	ds_read_b128 v[96:99], v254 offset:13856
	v_cvt_pk_f16_f32 v101, v15, v88
	v_cvt_pk_f16_f32 v107, v109, v160
	ds_read_b128 v[194:197], v254 offset:9216
	s_waitcnt lgkmcnt(1)
	v_mfma_f32_32x32x16_f16 v[48:63], v[96:99], v[162:165], v[48:63]
	ds_read_b128 v[96:99], v254 offset:13888
	s_xor_b32 s14, s14, 1
	s_mul_i32 s15, s14, 0x6c00
	s_sub_i32 s2, s2, 64
	s_mov_b64 s[8:9], 0x40000
	v_add_u32_e32 v146, s40, v146
	s_waitcnt lgkmcnt(0)
	v_mfma_f32_32x32x16_f16 v[48:63], v[96:99], v[100:103], v[48:63]
	ds_read_b128 v[96:99], v254 offset:13920
	v_add_f32_e32 v14, v92, v91
	v_fmac_f32_e32 v14, v189, v94
	ds_read_b128 v[88:91], v254 offset:18528
	v_add_u32_e32 v148, s40, v148
	v_add_u32_e32 v150, s40, v150
	v_add_u32_e32 v152, s40, v152
	s_waitcnt lgkmcnt(1)
	v_mfma_f32_32x32x16_f16 v[48:63], v[96:99], v[104:107], v[48:63]
	ds_read_b128 v[96:99], v254 offset:18432
	v_add_u32_e32 v154, s8, v154
	v_add_u32_e32 v156, s8, v156
	s_cmpk_lg_i32 s2, 0xf040
	v_mfma_f32_32x32x16_f16 v[64:79], v[194:197], v[190:193], v[64:79]
	ds_read_b128 v[194:197], v254 offset:9248
	s_waitcnt lgkmcnt(1)
	v_mfma_f32_32x32x16_f16 v[32:47], v[96:99], v[190:193], v[32:47]
	ds_read_b128 v[96:99], v254 offset:18464
	s_waitcnt lgkmcnt(1)
	v_mfma_f32_32x32x16_f16 v[64:79], v[194:197], v[162:165], v[64:79]
	ds_read_b128 v[194:197], v254 offset:9280
	s_waitcnt lgkmcnt(1)
	v_mfma_f32_32x32x16_f16 v[32:47], v[96:99], v[162:165], v[32:47]
	ds_read_b128 v[96:99], v254 offset:18496
	s_waitcnt lgkmcnt(1)
	v_mfma_f32_32x32x16_f16 v[64:79], v[194:197], v[100:103], v[64:79]
	ds_read_b128 v[194:197], v254 offset:9312
	s_waitcnt lgkmcnt(1)
	v_mfma_f32_32x32x16_f16 v[32:47], v[96:99], v[100:103], v[32:47]
	ds_read_b128 v[92:95], v254 offset:23040
	ds_read_b128 v[96:99], v254 offset:23072
	ds_read_b128 v[108:111], v254 offset:23104
	ds_read_b128 v[158:161], v254 offset:23136
	v_lshlrev_b32_e32 v0, 1, v171
	v_add3_u32 v0, s15, v0, v172
	s_waitcnt vmcnt(5)
	ds_write_b128 v0, v[6:9]
	v_lshlrev_b32_e32 v0, 1, v173
	v_add3_u32 v0, s15, v0, v174
	s_waitcnt vmcnt(4)
	ds_write_b128 v0, v[2:5]
	s_waitcnt lgkmcnt(5)
	v_mfma_f32_32x32x16_f16 v[16:31], v[92:95], v[190:193], v[16:31]
	v_lshlrev_b32_e32 v0, 1, v175
	v_add3_u32 v0, s15, v0, v144
	s_waitcnt vmcnt(3)
	v_add_u32_e32 v254, v252, v0
	ds_write2_b64 v254, v[128:129], v[130:131] offset1:2
	v_lshlrev_b32_e32 v0, 1, v182
	v_add3_u32 v0, s15, v0, v144
	s_waitcnt vmcnt(2)
	v_add_u32_e32 v255, v252, v0
	ds_write2_b64 v255, v[10:11], v[12:13] offset1:2
	v_lshlrev_b32_e32 v0, 1, v183
	s_waitcnt lgkmcnt(6)
	v_mfma_f32_32x32x16_f16 v[16:31], v[96:99], v[162:165], v[16:31]
	v_add3_u32 v0, s15, v0, v144
	s_waitcnt vmcnt(1)
	v_add_u32_e32 v254, v252, v0
	ds_write2_b64 v254, v[84:85], v[86:87] offset1:2
	v_lshlrev_b32_e32 v0, 1, v185
	v_add3_u32 v0, s15, v0, v144
	s_waitcnt vmcnt(0)
	v_add_u32_e32 v255, v252, v0
	ds_write2_b64 v255, v[80:81], v[82:83] offset1:2
	s_waitcnt lgkmcnt(0)
	s_barrier
	v_mfma_f32_32x32x16_f16 v[16:31], v[108:111], v[100:103], v[16:31]
	v_mfma_f32_32x32x16_f16 v[64:79], v[194:197], v[104:107], v[64:79]
	v_mfma_f32_32x32x16_f16 v[32:47], v[88:91], v[104:107], v[32:47]
	v_mfma_f32_32x32x16_f16 v[16:31], v[158:161], v[104:107], v[16:31]
	v_mov_b32_e32 v189, v14
	s_cbranch_scc1 .LBB0_1103
